# code placement: P1-P6 code moved by +4 bytes (s_nop at the P1 entry, compensated before P7 so later phases keep their offsets mod 64)
# speedup vs baseline: 1.0058x; 1.0058x over previous
; #define SEAM(k) do { if (IN(k) && IN((k) + 1)) { int zb = 0; asm volatile("" : "+s"(zb)); XcdBarrier bar; bar.bar = (unsigned*)((unsigned char*)args.in[I_WS + zb] + WS_CTL) + CW_BAR; bar.x = xb_xcc_id(); \
;         bar.st = (volatile LAS unsigned*)(lds + MISC_OFF) + 8; bar.t0 = (TIDW(wv0) == 0); xcd_barrier(bar); } } while (0)
; __device__ __forceinline__ void xcd_barrier(const XcdBarrier& b) {
;     ...
;     }
;     __syncthreads();
; __global__ void __launch_bounds__(NWAVES * 64, 2) hybrid_fwd(Args args) {
;     ...
;     SEAM(0);
.LBB0_136:
	s_or_b64 exec, exec, s[0:1]
	s_waitcnt lgkmcnt(0)
	s_barrier
	s_nop 0

; #define SEAM(k) do { if (IN(k) && IN((k) + 1)) { int zb = 0; asm volatile("" : "+s"(zb)); XcdBarrier bar; bar.bar = (unsigned*)((unsigned char*)args.in[I_WS + zb] + WS_CTL) + CW_BAR; bar.x = xb_xcc_id(); \
;         bar.st = (volatile LAS unsigned*)(lds + MISC_OFF) + 8; bar.t0 = (TIDW(wv0) == 0); xcd_barrier(bar); } } while (0)
; __device__ __forceinline__ void xcd_barrier(const XcdBarrier& b) {
;     ...
;     }
;     __syncthreads();
; __global__ void __launch_bounds__(NWAVES * 64, 2) hybrid_fwd(Args args) {
;     ...
;     SEAM(6);
.LBB0_1223:
	s_or_b64 exec, exec, s[2:3]
	s_waitcnt lgkmcnt(0)
	s_barrier
	s_nop 0
	s_nop 0
	s_nop 0
	s_nop 0
	s_nop 0
	s_nop 0
	s_nop 0
	s_nop 0
	s_nop 0
	s_nop 0
	s_nop 0
	s_nop 0
	s_nop 0
	s_nop 0
	s_nop 0
